# adds: block-diagonal up-projection GEMM runs only the non-zero K range per column tile (2 or 4 K-tiles instead of 6)
# speedup vs baseline: 1.0071x; 1.0047x over previous
.LBB0_620:
	s_or_b64 exec, exec, s[0:1]
	v_readlane_b32 s2, v253, 31
	s_waitcnt lgkmcnt(0)
	v_mov_b32_e32 v2, v207
	v_readlane_b32 s3, v253, 32
	s_barrier
	s_movk_i32 s0, 0x180
	s_andn2_b64 vcc, exec, s[2:3]
	v_readfirstlane_b32 s14, v2
	s_cbranch_vccnz .LBB0_641
	v_lshlrev_b32_e32 v1, 4, v2
	v_add_u32_e32 v3, 0x2000, v1
	v_ashrrev_i32_e32 v4, 31, v3
	v_lshrrev_b32_e32 v4, 22, v4
	v_add_u32_e32 v4, v3, v4
	v_ashrrev_i32_e32 v4, 10, v4
	v_mul_i32_i24_e32 v5, 0x400, v4
	v_sub_u32_e32 v3, v3, v5
	v_lshrrev_b32_e32 v5, 4, v3
	v_bitop3_b32 v5, v5, v3, 32 bitop3:0x6c
	v_ashrrev_i32_e32 v3, 31, v5
	v_lshrrev_b32_e32 v3, 26, v3
	v_add_u32_e32 v6, v5, v3
	v_lshlrev_b32_e32 v7, 3, v4
	v_ashrrev_i32_e32 v3, 6, v6
	v_and_b32_e32 v7, -16, v7
	v_add_u32_e32 v7, v3, v7
	v_and_b32_e32 v3, 3, v3
	s_mov_b32 s2, 0x7fffffe0
	v_lshrrev_b32_e32 v8, 2, v7
	v_lshlrev_b32_e32 v9, 1, v7
	v_and_or_b32 v3, v7, s2, v3
	v_and_b32_e32 v8, 4, v8
	v_and_b32_e32 v9, 24, v9
	v_or3_b32 v3, v3, v8, v9
	v_mul_lo_u32 v8, v3, s0
	v_lshlrev_b32_e32 v3, 5, v4
	v_and_b32_e32 v4, 0xc0, v6
	v_sub_u32_e32 v4, v5, v4
	v_ashrrev_i16_sdwa v4, v230, sext(v4) dst_sel:DWORD dst_unused:UNUSED_PAD src0_sel:DWORD src1_sel:BYTE_0
	v_and_b32_e32 v3, 32, v3
	v_bfe_i32 v4, v4, 0, 16
	v_add_u32_e32 v6, v3, v4
	v_mul_lo_u32 v5, v7, s0
	v_add_lshl_u32 v130, v8, v6, 1
	v_add_lshl_u32 v132, v6, v5, 1
	v_bfe_i32 v6, v2, 27, 1
	v_lshrrev_b32_e32 v6, 22, v6
	v_add_u32_e32 v6, v1, v6
	v_and_b32_e32 v6, 0xfffffc00, v6
	v_sub_u32_e32 v1, v1, v6
	v_lshrrev_b32_e32 v6, 4, v1
	v_ashrrev_i32_e32 v8, 31, v2
	v_bitop3_b32 v1, v6, v1, 32 bitop3:0x6c
	v_lshrrev_b32_e32 v8, 26, v8
	v_ashrrev_i32_e32 v6, 31, v1
	v_add_u32_e32 v8, v2, v8
	v_lshrrev_b32_e32 v6, 26, v6
	v_ashrrev_i32_e32 v8, 6, v8
	v_add_u32_e32 v7, v1, v6
	v_lshlrev_b32_e32 v9, 3, v8
	v_ashrrev_i32_e32 v6, 6, v7
	v_and_b32_e32 v9, -16, v9
	s_ashr_i32 s1, s0, 31
	v_add_u32_e32 v9, v6, v9
	v_and_b32_e32 v6, 3, v6
	s_lshl_b64 s[6:7], s[0:1], 9
	v_and_or_b32 v6, v9, s2, v6
	v_readlane_b32 s2, v254, 14
	v_readlane_b32 s9, v254, 13
	s_mul_i32 s2, s6, s2
	s_mul_hi_u32 s3, s6, s9
	s_add_i32 s8, s3, s2
	s_lshr_b64 s[2:3], s[0:1], 23
	v_readlane_b32 s16, v254, 0
	v_lshrrev_b32_e32 v10, 2, v9
	v_lshlrev_b32_e32 v11, 1, v9
	s_mul_i32 s3, s2, s9
	v_readlane_b32 s17, v254, 1
	v_and_b32_e32 v10, 4, v10
	v_and_b32_e32 v11, 24, v11
	v_and_b32_e32 v7, 0xc0, v7
	s_add_i32 s8, s8, s3
	s_mul_i32 s3, s6, s17
	s_mul_hi_u32 s10, s6, s16
	s_ashr_i32 s11, s14, 6
	v_or3_b32 v6, v6, v10, v11
	v_sub_u32_e32 v1, v1, v7
	s_add_i32 s3, s10, s3
	s_mul_i32 s2, s2, s16
	s_ashr_i32 s12, s14, 8
	s_lshl_b64 s[4:5], s[0:1], 8
	s_lshl_b32 s22, s11, 10
	v_mul_lo_u32 v10, v6, s0
	v_lshlrev_b32_e32 v6, 5, v8
	v_ashrrev_i16_sdwa v1, v230, sext(v1) dst_sel:DWORD dst_unused:UNUSED_PAD src0_sel:DWORD src1_sel:BYTE_0
	s_add_i32 s3, s3, s2
	s_mul_i32 s2, s6, s16
	v_readlane_b32 s10, v253, 29
	v_and_b32_e32 v6, 32, v6
	v_bfe_i32 v7, v1, 0, 16
	s_add_u32 s20, s10, s2
	v_readlane_b32 s2, v253, 30
	v_add_u32_e32 v1, v6, v7
	s_addc_u32 s21, s2, s3
	s_cmp_gt_u32 s16, 3
	s_cselect_b32 s2, 0x100, 0
	s_add_u32 s20, s20, s2
	s_addc_u32 s21, s21, 0
	s_add_i32 s23, s22, 0
	v_add_lshl_u32 v134, v10, v1, 1
	s_add_i32 m0, s23, 0x10000
	s_mul_i32 s9, s6, s9
	global_load_lds_dwordx4 v134, s[20:21]
	s_add_i32 m0, s23, 0x12000
	s_add_u32 s2, s20, s4
	global_load_lds_dwordx4 v130, s[20:21]
	s_addc_u32 s3, s21, s5
	s_add_i32 m0, s23, 0x14000
	v_readlane_b32 s10, v252, 59
	global_load_lds_dwordx4 v134, s[2:3]
	s_add_i32 m0, s23, 0x16000
	s_add_u32 s18, s10, s9
	v_readlane_b32 s9, v252, 60
	v_mul_lo_u32 v8, v9, s0
	s_addc_u32 s19, s9, s8
	s_cmp_gt_u32 s16, 3
	s_cselect_b32 s8, 0x100, 0
	s_add_u32 s18, s18, s8
	s_addc_u32 s19, s19, 0
	s_add_i32 s52, s23, 0x2000
	v_add_lshl_u32 v136, v1, v8, 1
	global_load_lds_dwordx4 v130, s[2:3]
	s_mov_b32 m0, s23
	s_add_u32 s8, s18, s4
	global_load_lds_dwordx4 v136, s[18:19]
	s_mov_b32 m0, s52
	s_addc_u32 s9, s19, s5
	s_add_i32 s53, s23, 0x4000
	global_load_lds_dwordx4 v132, s[18:19]
	s_mov_b32 m0, s53
	s_add_i32 s56, s23, 0x6000
	global_load_lds_dwordx4 v136, s[8:9]
	s_mov_b32 m0, s56
	s_cmp_eq_u32 s12, 1
	global_load_lds_dwordx4 v132, s[8:9]
	s_cselect_b64 s[8:9], -1, 0
	s_cmp_lg_u32 s12, 1
	s_cbranch_scc1 .LBB0_623
	s_barrier

.LBB0_626:
	s_cmp_lt_u32 s69, 4
	s_cselect_b32 s10, 2, 4
	s_cselect_b32 s11, 0, 2
	s_add_i32 s66, s66, 1
	s_mul_i32 s0, s66, s30
	s_mul_hi_u32 s1, s66, s26
	s_add_i32 s1, s1, s0
	s_mul_i32 s0, s66, s26
	s_add_u32 s0, s0, s24
	s_addc_u32 s1, s1, s25
	v_mov_b64_e32 v[2:3], 0x738
	v_cmp_lt_i64_e64 s[2:3], s[0:1], v[2:3]
	v_mov_b64_e32 v[2:3], 0x737
	v_cmp_gt_i64_e32 vcc, s[0:1], v[2:3]
	s_cbranch_vccnz .LBB0_628
	s_ashr_i32 s1, s0, 31
	s_lshr_b32 s1, s1, 29
	s_add_i32 s1, s0, s1
	s_ashr_i32 s16, s1, 3
	s_and_b32 s1, s1, -8
	s_sub_i32 s0, s0, s1
	s_cmp_lt_i32 s0, 0
	s_movk_i32 s1, 0xe8
	s_cselect_b32 s1, s1, 0xe7
	s_mul_i32 s0, s0, s1
	s_add_i32 s0, s0, s16
	s_mul_hi_i32 s1, s0, 0x92492493
	s_add_i32 s1, s1, s0
	s_lshr_b32 s16, s1, 31
	s_ashr_i32 s1, s1, 5
	s_add_i32 s1, s1, s16
	s_lshl_b32 s16, s1, 3
	s_sub_i32 s17, 0x108, s16
	s_min_i32 s17, s17, 8
	s_abs_i32 s31, s17
	v_cvt_f32_u32_e32 v2, s31
	s_sub_i32 s63, 0, s31
	s_mul_i32 s1, s1, 56
	s_sub_i32 s0, s0, s1
	v_rcp_iflag_f32_e32 v2, v2
	s_abs_i32 s1, s0
	s_xor_b32 s62, s0, s17
	s_ashr_i32 s62, s62, 31
	v_mul_f32_e32 v2, 0x4f7ffffe, v2
	v_cvt_u32_f32_e32 v2, v2
	s_nop 0
	v_readfirstlane_b32 s67, v2
	s_mul_i32 s63, s63, s67
	s_mul_hi_u32 s63, s67, s63
	s_add_i32 s67, s67, s63
	s_mul_hi_u32 s63, s1, s67
	s_mul_i32 s67, s63, s31
	s_sub_i32 s1, s1, s67
	s_add_i32 s68, s63, 1
	s_sub_i32 s67, s1, s31
	s_cmp_ge_u32 s1, s31
	s_cselect_b32 s63, s68, s63
	s_cselect_b32 s1, s67, s1
	s_add_i32 s67, s63, 1
	s_cmp_ge_u32 s1, s31
	s_cselect_b32 s1, s67, s63
	s_xor_b32 s1, s1, s62
	s_sub_i32 s67, s1, s62
	s_mul_i32 s1, s67, s17
	s_sub_i32 s0, s0, s1
	s_add_i32 s68, s16, s0
.LBB0_628:
	v_cndmask_b32_e64 v2, 0, 1, s[2:3]
	v_cmp_ne_u32_e64 s[0:1], 1, v2
	s_andn2_b64 vcc, exec, s[2:3]
	s_mov_b64 s[2:3], s[18:19]
	s_cbranch_vccnz .LBB0_630
	s_ashr_i32 s2, s68, 31
	s_mul_hi_u32 s3, s6, s68
	s_mul_i32 s2, s6, s2
	s_add_i32 s2, s3, s2
	s_mul_i32 s3, s7, s68
	s_add_i32 s3, s2, s3
	s_mul_i32 s2, s6, s68
	v_readlane_b32 s16, v252, 59
	s_add_u32 s2, s16, s2
	v_readlane_b32 s16, v252, 60
	s_addc_u32 s3, s16, s3
	s_cmp_gt_u32 s67, 3
	s_cselect_b32 s62, 0x100, 0
	s_add_u32 s2, s2, s62
	s_addc_u32 s3, s3, 0
.LBB0_630:
	s_and_b64 vcc, exec, s[0:1]
	s_mov_b64 s[16:17], s[20:21]
	s_cbranch_vccnz .LBB0_632
	s_ashr_i32 s16, s67, 31
	s_mul_hi_u32 s17, s6, s67
	s_mul_i32 s16, s6, s16
	s_add_i32 s16, s17, s16
	s_mul_i32 s17, s7, s67
	s_add_i32 s17, s16, s17
	s_mul_i32 s16, s6, s67
	v_readlane_b32 s31, v253, 29
	s_add_u32 s16, s31, s16
	v_readlane_b32 s31, v253, 30
	s_addc_u32 s17, s31, s17
	s_cmp_gt_u32 s67, 3
	s_cselect_b32 s62, 0x100, 0
	s_add_u32 s16, s16, s62
	s_addc_u32 s17, s17, 0
